# attention chunk loop: scalar branch skips the window-mask exec logic on non-window chunks
# baseline (speedup 1.0000x reference)
.Lg_ld:
	global_load_dwordx4 v[126:129], v[34:35], off offset:-2048
	global_load_dwordx4 v[122:125], v[34:35], off offset:2048
	global_load_dwordx4 v[118:121], v[36:37], off offset:-2048
	global_load_dwordx4 v[114:117], v[36:37], off offset:2048
	s_cmp_gt_u32 s3, 7
	s_cselect_b64 s[72:73], -1, 0
	s_and_b64 s[94:95], s[0:1], s[72:73]
	v_mov_b32_e32 v66, 0
	s_mov_b64 vcc, -1
	s_cbranch_scc0 .Lattn_nowin
	s_and_saveexec_b64 s[76:77], s[94:95]
	v_add_u32_e32 v34, s3, v189
	v_cmp_ge_i32_e32 vcc, v34, v182
	v_cmp_lt_i32_e64 s[72:73], v34, v186
	s_and_b64 s[72:73], vcc, s[72:73]
	s_orn2_b64 vcc, s[72:73], exec
	v_mov_b32_e32 v66, v188
	s_or_b64 exec, exec, s[76:77]
.Lattn_nowin:
	s_and_saveexec_b64 s[72:73], vcc
	s_cbranch_execz .LBB0_475
	s_bitcmp1_b32 s3, 0
	s_cselect_b32 s3, 0x4800, 0
	v_add_u32_e32 v137, s3, v173
	ds_read_b128 v[192:195], v137
	ds_read_b128 v[208:211], v137 offset:4608
	ds_read_b128 v[196:199], v137 offset:32
	ds_read_b128 v[214:217], v137 offset:4640
	ds_read_b128 v[200:203], v137 offset:64
	ds_read_b128 v[218:221], v137 offset:4672
	ds_read_b128 v[204:207], v137 offset:96
	ds_read_b128 v[222:225], v137 offset:4704
	s_waitcnt lgkmcnt(6)
	v_mfma_f32_32x32x16_bf16 v[50:65], v[192:195], v[98:101], 0
	v_mfma_f32_32x32x16_bf16 v[34:49], v[208:211], v[98:101], 0
	s_waitcnt lgkmcnt(4)
	v_mfma_f32_32x32x16_bf16 v[50:65], v[196:199], v[102:105], v[50:65]
	v_mfma_f32_32x32x16_bf16 v[34:49], v[214:217], v[102:105], v[34:49]
	s_waitcnt lgkmcnt(2)
	v_mfma_f32_32x32x16_bf16 v[50:65], v[200:203], v[106:109], v[50:65]
	v_mfma_f32_32x32x16_bf16 v[34:49], v[218:221], v[106:109], v[34:49]
	s_waitcnt lgkmcnt(0)
	v_mfma_f32_32x32x16_bf16 v[50:65], v[204:207], v[110:113], v[50:65]
	v_mfma_f32_32x32x16_bf16 v[34:49], v[222:225], v[110:113], v[34:49]
	ds_read_b128 v[192:195], v137 offset:9216
	ds_read_b128 v[208:211], v137 offset:13824
	ds_read_b128 v[196:199], v137 offset:9248
	ds_read_b128 v[214:217], v137 offset:13856
	ds_read_b128 v[200:203], v137 offset:9280
	ds_read_b128 v[218:221], v137 offset:13888
	ds_read_b128 v[204:207], v137 offset:9312
	ds_read_b128 v[222:225], v137 offset:13920
	s_and_saveexec_b64 vcc, s[94:95]
	s_cbranch_execz .LBB0_549
	v_lshl_add_u32 v141, v66, 2, v187
	v_add_u32_e32 v141, 0x903c, v141
	v_mov_b32_e32 v246, 0xff800000
	v_readfirstlane_b32 s98, v212
	s_nop 0
	s_bitcmp1_b32 s98, 6
	s_cbranch_scc1 .Lwin_odd
	s_branch .Lwin_even
